# v113 + layer 0's first FFN starts in chain mode: two-pass SwiGLU and XCD-local barriers replace the grid sync between the first SwiGLU GEMM and its down-projection
# speedup vs baseline: 1.0053x; 1.0053x over previous
; #define GLOBAL_PTR(T, p) ((T*)(__attribute__((address_space(1))) T*)(launder_u64((unsigned long long)(p))))
; __global__ void __launch_bounds__(512, 2) fwd_megakernel(Args args) {
;     ...
;         for (int op = 0; op < 14; ++op) {
;             { int t_ = threadIdx.x; asm volatile("" : "+v"(t_)); F.tid = t_; F.lane = t_ & 63; F.wave = __builtin_amdgcn_readfirstlane(t_ >> 6);
;               unsigned char* w_ = args.ws; asm volatile("" : "+s"(w_)); F.ws = GLOBAL_PTR(unsigned char, w_); float* o_ = args.out; asm volatile("" : "+s"(o_)); F.out = GLOBAL_PTR(float, o_);
;               int g_ = gridDim.x, b_ = blockIdx.x; asm volatile("" : "+s"(g_), "+s"(b_)); F.G = g_; bx = b_; F.vcu = (g_ % 8 == 0) ? (b_ % 8) * (g_ / 8) + b_ / 8 : b_; }
;             bf16_t* H = WSP(bf16_t, WS_H); bf16_t* BIG = WSP(bf16_t, WS_BIG); float* XC = WSP(float, WS_XC);
;             const float* modl = WSP(float, WS_MOD) + (size_t)l * NBI * MODW;
;             const int opq = ((op == 6 || op == 7) && (bx & 1)) ? 13 - op : op;
;             int type = T_NOP;
;             const bool skip0 = (l == 0 && op == 0);
;             if (op == 0 || op == 3 || op == 11) type = skip0 ? T_NOP : T_NORM;
.LBB0_585:
	s_mov_b32 s48, 0xf800000
	s_or_b32 s4, s36, s44
	s_cmp_eq_u32 s4, 0
	s_cbranch_scc0 .Ll0_skip
	s_cmp_eq_u32 s13, 0x100
	s_cbranch_scc0 .Ll0_skip
	s_mov_b32 s98, 3
.Ll0_skip:
	s_add_i32 s44, s44, 1
	s_cmp_eq_u32 s44, 14
	s_cbranch_scc0 .LBB0_188
	s_branch .LBB0_184
